# mirrored: static s_setprio 1 for waves 0-3 (leading half) instead of waves 4-7, flips deleted
# baseline (speedup 1.0000x reference)
; template <class Epi, class Sched, bool ALIGN_EPI = false, bool SP2 = false>
; __device__ __forceinline__ void gemm_phase(PG8_LAS unsigned char* lds, const Gemm g, const Sched& S, const Epi& E, const int tid_in) {
;     ...
; #pragma unroll
;         for (int a = 0; a < 2; ++a)
; #pragma unroll
;             for (int b = 0; b < 2; ++b)
; #pragma unroll
;                 for (int m = 0; m < 4; ++m)
; #pragma unroll
;                     for (int n = 0; n < 2; ++n) acc[a][b][m][n] = (f32x4){0.f, 0.f, 0.f, 0.f};
;         cur = nxt; cA = nA; cB = nB; ++ui;
.LBB0_119:
	s_add_u32 s56, s8, 0x100
	v_mov_b32_e32 v0, 0
	s_addc_u32 s57, s9, 0
	s_mov_b32 s58, -2
	v_mov_b32_e32 v1, v0
	v_mov_b32_e32 v2, v0
	v_mov_b32_e32 v3, v0
	v_mov_b32_e32 v4, v0
	v_mov_b32_e32 v5, v0
	v_mov_b32_e32 v6, v0
	v_mov_b32_e32 v7, v0
	v_mov_b32_e32 v8, v0
	v_mov_b32_e32 v9, v0
	v_mov_b32_e32 v10, v0
	v_mov_b32_e32 v11, v0
	v_mov_b32_e32 v16, v0
	v_mov_b32_e32 v17, v0
	v_mov_b32_e32 v18, v0
	v_mov_b32_e32 v19, v0
	v_mov_b32_e32 v24, v0
	v_mov_b32_e32 v25, v0
	v_mov_b32_e32 v26, v0
	v_mov_b32_e32 v27, v0
	v_mov_b32_e32 v32, v0
	v_mov_b32_e32 v33, v0
	v_mov_b32_e32 v34, v0
	v_mov_b32_e32 v35, v0
	v_mov_b32_e32 v40, v0
	v_mov_b32_e32 v41, v0
	v_mov_b32_e32 v42, v0
	v_mov_b32_e32 v43, v0
	v_mov_b32_e32 v48, v0
	v_mov_b32_e32 v49, v0
	v_mov_b32_e32 v50, v0
	v_mov_b32_e32 v51, v0
	v_mov_b32_e32 v12, v0
	v_mov_b32_e32 v13, v0
	v_mov_b32_e32 v14, v0
	v_mov_b32_e32 v15, v0
	v_mov_b32_e32 v20, v0
	v_mov_b32_e32 v21, v0
	v_mov_b32_e32 v22, v0
	v_mov_b32_e32 v23, v0
	v_mov_b32_e32 v28, v0
	v_mov_b32_e32 v29, v0
	v_mov_b32_e32 v30, v0
	v_mov_b32_e32 v31, v0
	v_mov_b32_e32 v36, v0
	v_mov_b32_e32 v37, v0
	v_mov_b32_e32 v38, v0
	v_mov_b32_e32 v39, v0
	v_mov_b32_e32 v44, v0
	v_mov_b32_e32 v45, v0
	v_mov_b32_e32 v46, v0
	v_mov_b32_e32 v47, v0
	v_mov_b32_e32 v52, v0
	v_mov_b32_e32 v53, v0
	v_mov_b32_e32 v54, v0
	v_mov_b32_e32 v55, v0
	v_mov_b32_e32 v56, v0
	v_mov_b32_e32 v57, v0
	v_mov_b32_e32 v58, v0
	v_mov_b32_e32 v59, v0
	v_mov_b32_e32 v60, v0
	v_mov_b32_e32 v61, v0
	v_mov_b32_e32 v62, v0
	v_mov_b32_e32 v63, v0
	v_mov_b32_e32 v64, v0
	v_mov_b32_e32 v65, v0
	v_mov_b32_e32 v66, v0
	v_mov_b32_e32 v67, v0
	v_mov_b32_e32 v68, v0
	v_mov_b32_e32 v69, v0
	v_mov_b32_e32 v70, v0
	v_mov_b32_e32 v71, v0
	v_mov_b32_e32 v80, v0
	v_mov_b32_e32 v81, v0
	v_mov_b32_e32 v82, v0
	v_mov_b32_e32 v83, v0
	v_mov_b32_e32 v84, v0
	v_mov_b32_e32 v85, v0
	v_mov_b32_e32 v86, v0
	v_mov_b32_e32 v87, v0
	v_mov_b32_e32 v98, v0
	v_mov_b32_e32 v99, v0
	v_mov_b32_e32 v100, v0
	v_mov_b32_e32 v101, v0
	v_mov_b32_e32 v102, v0
	v_mov_b32_e32 v103, v0
	v_mov_b32_e32 v104, v0
	v_mov_b32_e32 v105, v0
	v_mov_b32_e32 v130, v0
	v_mov_b32_e32 v131, v0
	v_mov_b32_e32 v132, v0
	v_mov_b32_e32 v133, v0
	v_mov_b32_e32 v134, v0
	v_mov_b32_e32 v135, v0
	v_mov_b32_e32 v136, v0
	v_mov_b32_e32 v137, v0
	v_mov_b32_e32 v72, v0
	v_mov_b32_e32 v73, v0
	v_mov_b32_e32 v74, v0
	v_mov_b32_e32 v75, v0
	v_mov_b32_e32 v76, v0
	v_mov_b32_e32 v77, v0
	v_mov_b32_e32 v78, v0
	v_mov_b32_e32 v79, v0
	v_mov_b32_e32 v88, v0
	v_mov_b32_e32 v89, v0
	v_mov_b32_e32 v90, v0
	v_mov_b32_e32 v91, v0
	v_mov_b32_e32 v92, v0
	v_mov_b32_e32 v93, v0
	v_mov_b32_e32 v94, v0
	v_mov_b32_e32 v95, v0
	v_mov_b32_e32 v106, v0
	v_mov_b32_e32 v107, v0
	v_mov_b32_e32 v108, v0
	v_mov_b32_e32 v109, v0
	v_mov_b32_e32 v110, v0
	v_mov_b32_e32 v111, v0
	v_mov_b32_e32 v112, v0
	v_mov_b32_e32 v113, v0
	v_mov_b32_e32 v138, v0
	v_mov_b32_e32 v139, v0
	v_mov_b32_e32 v140, v0
	v_mov_b32_e32 v141, v0
	v_mov_b32_e32 v142, v0
	v_mov_b32_e32 v143, v0
	v_mov_b32_e32 v144, v0
	v_mov_b32_e32 v145, v0
	v_readfirstlane_b32 s70, v241
	s_nop 3
	s_lshr_b32 s70, s70, 6
	s_cmp_lt_u32 s70, 4
	s_cbranch_scc0 .Lprio_done_120
	s_setprio 1

; template <class Epi, class Sched, bool ALIGN_EPI = false, bool SP2 = false>
; __device__ __forceinline__ void gemm_phase(PG8_LAS unsigned char* lds, const Gemm g, const Sched& S, const Epi& E, const int tid_in) {
;     ...
;         const bool has_next = S.next(ui + 1, nxt);
;         const char* nA = has_next ? (const char*)g.A + (size_t)nxt.pm * tstep : cA; const char* nB = has_next ? (const char*)g.Bt + (size_t)nxt.pn * tstep : cB;
;     ...
; #pragma unroll
;         for (int a = 0; a < 2; ++a)
; #pragma unroll
;             for (int b = 0; b < 2; ++b)
; #pragma unroll
;                 for (int m = 0; m < 4; ++m)
; #pragma unroll
;                     for (int n = 0; n < 2; ++n) acc[a][b][m][n] = (f32x4){0.f, 0.f, 0.f, 0.f};
;         cur = nxt; cA = nA; cB = nB; ++ui;
.LBB0_137:
	s_ashr_i32 s43, s42, 31
	s_lshl_b64 s[12:13], s[42:43], 20
	v_readlane_b32 s44, v255, 4
	v_readlane_b32 s45, v255, 5
	s_add_u32 s44, s44, s12
	s_addc_u32 s45, s45, s13
	s_and_b64 s[12:13], s[38:39], exec
	s_cselect_b32 s12, s45, s11
	s_cselect_b32 s13, s44, s10
	s_ashr_i32 s41, s40, 31
	s_lshl_b64 s[48:49], s[40:41], 20
	s_add_u32 s48, s14, s48
	s_addc_u32 s49, s15, s49
	s_and_b64 s[50:51], s[38:39], exec
	s_cselect_b32 s41, s49, s9
	s_cselect_b32 s43, s48, s8
	s_add_u32 s50, s10, 0x80080
	s_addc_u32 s51, s11, 0
	s_add_u32 s56, s8, 0x100
	v_mov_b32_e32 v0, 0
	s_addc_u32 s57, s9, 0
	s_mov_b32 s58, -2
	v_mov_b32_e32 v1, v0
	v_mov_b32_e32 v2, v0
	v_mov_b32_e32 v3, v0
	v_mov_b32_e32 v8, v0
	v_mov_b32_e32 v9, v0
	v_mov_b32_e32 v10, v0
	v_mov_b32_e32 v11, v0
	v_mov_b32_e32 v16, v0
	v_mov_b32_e32 v17, v0
	v_mov_b32_e32 v18, v0
	v_mov_b32_e32 v19, v0
	v_mov_b32_e32 v24, v0
	v_mov_b32_e32 v25, v0
	v_mov_b32_e32 v26, v0
	v_mov_b32_e32 v27, v0
	v_mov_b32_e32 v32, v0
	v_mov_b32_e32 v33, v0
	v_mov_b32_e32 v34, v0
	v_mov_b32_e32 v35, v0
	v_mov_b32_e32 v40, v0
	v_mov_b32_e32 v41, v0
	v_mov_b32_e32 v42, v0
	v_mov_b32_e32 v43, v0
	v_mov_b32_e32 v48, v0
	v_mov_b32_e32 v49, v0
	v_mov_b32_e32 v50, v0
	v_mov_b32_e32 v51, v0
	v_mov_b32_e32 v56, v0
	v_mov_b32_e32 v57, v0
	v_mov_b32_e32 v58, v0
	v_mov_b32_e32 v59, v0
	v_mov_b32_e32 v4, v0
	v_mov_b32_e32 v5, v0
	v_mov_b32_e32 v6, v0
	v_mov_b32_e32 v7, v0
	v_mov_b32_e32 v12, v0
	v_mov_b32_e32 v13, v0
	v_mov_b32_e32 v14, v0
	v_mov_b32_e32 v15, v0
	v_mov_b32_e32 v20, v0
	v_mov_b32_e32 v21, v0
	v_mov_b32_e32 v22, v0
	v_mov_b32_e32 v23, v0
	v_mov_b32_e32 v28, v0
	v_mov_b32_e32 v29, v0
	v_mov_b32_e32 v30, v0
	v_mov_b32_e32 v31, v0
	v_mov_b32_e32 v36, v0
	v_mov_b32_e32 v37, v0
	v_mov_b32_e32 v38, v0
	v_mov_b32_e32 v39, v0
	v_mov_b32_e32 v44, v0
	v_mov_b32_e32 v45, v0
	v_mov_b32_e32 v46, v0
	v_mov_b32_e32 v47, v0
	v_mov_b32_e32 v52, v0
	v_mov_b32_e32 v53, v0
	v_mov_b32_e32 v54, v0
	v_mov_b32_e32 v55, v0
	v_mov_b32_e32 v60, v0
	v_mov_b32_e32 v61, v0
	v_mov_b32_e32 v62, v0
	v_mov_b32_e32 v63, v0
	v_mov_b32_e32 v64, v0
	v_mov_b32_e32 v65, v0
	v_mov_b32_e32 v66, v0
	v_mov_b32_e32 v67, v0
	v_mov_b32_e32 v72, v0
	v_mov_b32_e32 v73, v0
	v_mov_b32_e32 v74, v0
	v_mov_b32_e32 v75, v0
	v_mov_b32_e32 v80, v0
	v_mov_b32_e32 v81, v0
	v_mov_b32_e32 v82, v0
	v_mov_b32_e32 v83, v0
	v_mov_b32_e32 v88, v0
	v_mov_b32_e32 v89, v0
	v_mov_b32_e32 v90, v0
	v_mov_b32_e32 v91, v0
	v_mov_b32_e32 v98, v0
	v_mov_b32_e32 v99, v0
	v_mov_b32_e32 v100, v0
	v_mov_b32_e32 v101, v0
	v_mov_b32_e32 v106, v0
	v_mov_b32_e32 v107, v0
	v_mov_b32_e32 v108, v0
	v_mov_b32_e32 v109, v0
	v_mov_b32_e32 v114, v0
	v_mov_b32_e32 v115, v0
	v_mov_b32_e32 v116, v0
	v_mov_b32_e32 v117, v0
	v_mov_b32_e32 v122, v0
	v_mov_b32_e32 v123, v0
	v_mov_b32_e32 v124, v0
	v_mov_b32_e32 v125, v0
	v_mov_b32_e32 v68, v0
	v_mov_b32_e32 v69, v0
	v_mov_b32_e32 v70, v0
	v_mov_b32_e32 v71, v0
	v_mov_b32_e32 v76, v0
	v_mov_b32_e32 v77, v0
	v_mov_b32_e32 v78, v0
	v_mov_b32_e32 v79, v0
	v_mov_b32_e32 v84, v0
	v_mov_b32_e32 v85, v0
	v_mov_b32_e32 v86, v0
	v_mov_b32_e32 v87, v0
	v_mov_b32_e32 v92, v0
	v_mov_b32_e32 v93, v0
	v_mov_b32_e32 v94, v0
	v_mov_b32_e32 v95, v0
	v_mov_b32_e32 v102, v0
	v_mov_b32_e32 v103, v0
	v_mov_b32_e32 v104, v0
	v_mov_b32_e32 v105, v0
	v_mov_b32_e32 v110, v0
	v_mov_b32_e32 v111, v0
	v_mov_b32_e32 v112, v0
	v_mov_b32_e32 v113, v0
	v_mov_b32_e32 v118, v0
	v_mov_b32_e32 v119, v0
	v_mov_b32_e32 v120, v0
	v_mov_b32_e32 v121, v0
	v_mov_b32_e32 v126, v0
	v_mov_b32_e32 v127, v0
	v_mov_b32_e32 v128, v0
	v_mov_b32_e32 v129, v0
	v_readfirstlane_b32 s70, v241
	s_nop 3
	s_lshr_b32 s70, s70, 6
	s_cmp_lt_u32 s70, 4
	s_cbranch_scc0 .Lprio_done_138
	s_setprio 1

; template <class Epi, class Sched, bool ALIGN_EPI = false, bool SP2 = false>
; __device__ __forceinline__ void gemm_phase(PG8_LAS unsigned char* lds, const Gemm g, const Sched& S, const Epi& E, const int tid_in) {
;     ...
;         const bool has_next = S.next(ui + 1, nxt);
;         const char* nA = has_next ? (const char*)g.A + (size_t)nxt.pm * tstep : cA; const char* nB = has_next ? (const char*)g.Bt + (size_t)nxt.pn * tstep : cB;
;     ...
; #pragma unroll
;         for (int a = 0; a < 2; ++a)
; #pragma unroll
;             for (int b = 0; b < 2; ++b)
; #pragma unroll
;                 for (int m = 0; m < 4; ++m)
; #pragma unroll
;                     for (int n = 0; n < 2; ++n) acc[a][b][m][n] = (f32x4){0.f, 0.f, 0.f, 0.f};
;         cur = nxt; cA = nA; cB = nB; ++ui;
.LBB0_179:
	s_ashr_i32 s43, s42, 31
	s_lshl_b64 s[12:13], s[42:43], 20
	v_readlane_b32 s44, v255, 4
	v_readlane_b32 s45, v255, 5
	s_add_u32 s44, s44, s12
	s_addc_u32 s45, s45, s13
	s_and_b64 s[12:13], s[38:39], exec
	s_cselect_b32 s12, s45, s11
	s_cselect_b32 s13, s44, s10
	s_ashr_i32 s41, s40, 31
	s_lshl_b64 s[48:49], s[40:41], 20
	s_add_u32 s48, s14, s48
	s_addc_u32 s49, s15, s49
	s_and_b64 s[50:51], s[38:39], exec
	s_cselect_b32 s41, s49, s9
	s_cselect_b32 s43, s48, s8
	s_add_u32 s50, s10, 0x80080
	s_addc_u32 s51, s11, 0
	s_add_u32 s58, s8, 0x100
	v_mov_b32_e32 v0, 0
	s_addc_u32 s59, s9, 0
	s_mov_b32 s60, -2
	v_mov_b32_e32 v1, v0
	v_mov_b32_e32 v2, v0
	v_mov_b32_e32 v3, v0
	v_mov_b32_e32 v4, v0
	v_mov_b32_e32 v5, v0
	v_mov_b32_e32 v6, v0
	v_mov_b32_e32 v7, v0
	v_mov_b32_e32 v8, v0
	v_mov_b32_e32 v9, v0
	v_mov_b32_e32 v10, v0
	v_mov_b32_e32 v11, v0
	v_mov_b32_e32 v16, v0
	v_mov_b32_e32 v17, v0
	v_mov_b32_e32 v18, v0
	v_mov_b32_e32 v19, v0
	v_mov_b32_e32 v24, v0
	v_mov_b32_e32 v25, v0
	v_mov_b32_e32 v26, v0
	v_mov_b32_e32 v27, v0
	v_mov_b32_e32 v32, v0
	v_mov_b32_e32 v33, v0
	v_mov_b32_e32 v34, v0
	v_mov_b32_e32 v35, v0
	v_mov_b32_e32 v40, v0
	v_mov_b32_e32 v41, v0
	v_mov_b32_e32 v42, v0
	v_mov_b32_e32 v43, v0
	v_mov_b32_e32 v48, v0
	v_mov_b32_e32 v49, v0
	v_mov_b32_e32 v50, v0
	v_mov_b32_e32 v51, v0
	v_mov_b32_e32 v12, v0
	v_mov_b32_e32 v13, v0
	v_mov_b32_e32 v14, v0
	v_mov_b32_e32 v15, v0
	v_mov_b32_e32 v20, v0
	v_mov_b32_e32 v21, v0
	v_mov_b32_e32 v22, v0
	v_mov_b32_e32 v23, v0
	v_mov_b32_e32 v28, v0
	v_mov_b32_e32 v29, v0
	v_mov_b32_e32 v30, v0
	v_mov_b32_e32 v31, v0
	v_mov_b32_e32 v36, v0
	v_mov_b32_e32 v37, v0
	v_mov_b32_e32 v38, v0
	v_mov_b32_e32 v39, v0
	v_mov_b32_e32 v44, v0
	v_mov_b32_e32 v45, v0
	v_mov_b32_e32 v46, v0
	v_mov_b32_e32 v47, v0
	v_mov_b32_e32 v52, v0
	v_mov_b32_e32 v53, v0
	v_mov_b32_e32 v54, v0
	v_mov_b32_e32 v55, v0
	v_mov_b32_e32 v56, v0
	v_mov_b32_e32 v57, v0
	v_mov_b32_e32 v58, v0
	v_mov_b32_e32 v59, v0
	v_mov_b32_e32 v60, v0
	v_mov_b32_e32 v61, v0
	v_mov_b32_e32 v62, v0
	v_mov_b32_e32 v63, v0
	v_mov_b32_e32 v64, v0
	v_mov_b32_e32 v65, v0
	v_mov_b32_e32 v66, v0
	v_mov_b32_e32 v67, v0
	v_mov_b32_e32 v68, v0
	v_mov_b32_e32 v69, v0
	v_mov_b32_e32 v70, v0
	v_mov_b32_e32 v71, v0
	v_mov_b32_e32 v80, v0
	v_mov_b32_e32 v81, v0
	v_mov_b32_e32 v82, v0
	v_mov_b32_e32 v83, v0
	v_mov_b32_e32 v84, v0
	v_mov_b32_e32 v85, v0
	v_mov_b32_e32 v86, v0
	v_mov_b32_e32 v87, v0
	v_mov_b32_e32 v98, v0
	v_mov_b32_e32 v99, v0
	v_mov_b32_e32 v100, v0
	v_mov_b32_e32 v101, v0
	v_mov_b32_e32 v102, v0
	v_mov_b32_e32 v103, v0
	v_mov_b32_e32 v104, v0
	v_mov_b32_e32 v105, v0
	v_mov_b32_e32 v130, v0
	v_mov_b32_e32 v131, v0
	v_mov_b32_e32 v132, v0
	v_mov_b32_e32 v133, v0
	v_mov_b32_e32 v134, v0
	v_mov_b32_e32 v135, v0
	v_mov_b32_e32 v136, v0
	v_mov_b32_e32 v137, v0
	v_mov_b32_e32 v72, v0
	v_mov_b32_e32 v73, v0
	v_mov_b32_e32 v74, v0
	v_mov_b32_e32 v75, v0
	v_mov_b32_e32 v76, v0
	v_mov_b32_e32 v77, v0
	v_mov_b32_e32 v78, v0
	v_mov_b32_e32 v79, v0
	v_mov_b32_e32 v88, v0
	v_mov_b32_e32 v89, v0
	v_mov_b32_e32 v90, v0
	v_mov_b32_e32 v91, v0
	v_mov_b32_e32 v92, v0
	v_mov_b32_e32 v93, v0
	v_mov_b32_e32 v94, v0
	v_mov_b32_e32 v95, v0
	v_mov_b32_e32 v106, v0
	v_mov_b32_e32 v107, v0
	v_mov_b32_e32 v108, v0
	v_mov_b32_e32 v109, v0
	v_mov_b32_e32 v110, v0
	v_mov_b32_e32 v111, v0
	v_mov_b32_e32 v112, v0
	v_mov_b32_e32 v113, v0
	v_mov_b32_e32 v138, v0
	v_mov_b32_e32 v139, v0
	v_mov_b32_e32 v140, v0
	v_mov_b32_e32 v141, v0
	v_mov_b32_e32 v142, v0
	v_mov_b32_e32 v143, v0
	v_mov_b32_e32 v144, v0
	v_mov_b32_e32 v145, v0
	v_readfirstlane_b32 s70, v241
	s_nop 3
	s_lshr_b32 s70, s70, 6
	s_cmp_lt_u32 s70, 4
	s_cbranch_scc0 .Lprio_done_180
	s_setprio 1

; template <class Epi, class Sched, bool ALIGN_EPI = false, bool SP2 = false>
; __device__ __forceinline__ void gemm_phase(PG8_LAS unsigned char* lds, const Gemm g, const Sched& S, const Epi& E, const int tid_in) {
;     ...
;         const bool has_next = S.next(ui + 1, nxt);
;         const char* nA = has_next ? (const char*)g.A + (size_t)nxt.pm * tstep : cA; const char* nB = has_next ? (const char*)g.Bt + (size_t)nxt.pn * tstep : cB;
;     ...
; #pragma unroll
;         for (int a = 0; a < 2; ++a)
; #pragma unroll
;             for (int b = 0; b < 2; ++b)
; #pragma unroll
;                 for (int m = 0; m < 4; ++m)
; #pragma unroll
;                     for (int n = 0; n < 2; ++n) acc[a][b][m][n] = (f32x4){0.f, 0.f, 0.f, 0.f};
;         cur = nxt; cA = nA; cB = nB; ++ui;
.LBB0_592:
	s_ashr_i32 s57, s56, 31
	s_lshl_b64 s[12:13], s[56:57], 20
	v_readlane_b32 s36, v255, 4
	v_readlane_b32 s37, v255, 5
	s_add_u32 s36, s36, s12
	s_addc_u32 s37, s37, s13
	s_and_b64 s[12:13], s[38:39], exec
	s_cselect_b32 s12, s37, s11
	s_cselect_b32 s13, s36, s10
	s_ashr_i32 s55, s54, 31
	s_lshl_b64 s[42:43], s[54:55], 20
	s_add_u32 s58, s14, s42
	s_addc_u32 s59, s15, s43
	s_and_b64 s[42:43], s[38:39], exec
	s_cselect_b32 s41, s59, s9
	s_cselect_b32 s44, s58, s8
	s_add_u32 s42, s10, 0x80080
	s_addc_u32 s43, s11, 0
	s_add_u32 s45, s8, 0x100
	v_mov_b32_e32 v0, 0
	s_addc_u32 s55, s9, 0
	s_mov_b32 s57, -2
	v_mov_b32_e32 v1, v0
	v_mov_b32_e32 v2, v0
	v_mov_b32_e32 v3, v0
	v_mov_b32_e32 v4, v0
	v_mov_b32_e32 v5, v0
	v_mov_b32_e32 v6, v0
	v_mov_b32_e32 v7, v0
	v_mov_b32_e32 v16, v0
	v_mov_b32_e32 v17, v0
	v_mov_b32_e32 v18, v0
	v_mov_b32_e32 v19, v0
	v_mov_b32_e32 v20, v0
	v_mov_b32_e32 v21, v0
	v_mov_b32_e32 v22, v0
	v_mov_b32_e32 v23, v0
	v_mov_b32_e32 v32, v0
	v_mov_b32_e32 v33, v0
	v_mov_b32_e32 v34, v0
	v_mov_b32_e32 v35, v0
	v_mov_b32_e32 v36, v0
	v_mov_b32_e32 v37, v0
	v_mov_b32_e32 v38, v0
	v_mov_b32_e32 v39, v0
	v_mov_b32_e32 v48, v0
	v_mov_b32_e32 v49, v0
	v_mov_b32_e32 v50, v0
	v_mov_b32_e32 v51, v0
	v_mov_b32_e32 v52, v0
	v_mov_b32_e32 v53, v0
	v_mov_b32_e32 v54, v0
	v_mov_b32_e32 v55, v0
	v_mov_b32_e32 v8, v0
	v_mov_b32_e32 v9, v0
	v_mov_b32_e32 v10, v0
	v_mov_b32_e32 v11, v0
	v_mov_b32_e32 v12, v0
	v_mov_b32_e32 v13, v0
	v_mov_b32_e32 v14, v0
	v_mov_b32_e32 v15, v0
	v_mov_b32_e32 v24, v0
	v_mov_b32_e32 v25, v0
	v_mov_b32_e32 v26, v0
	v_mov_b32_e32 v27, v0
	v_mov_b32_e32 v28, v0
	v_mov_b32_e32 v29, v0
	v_mov_b32_e32 v30, v0
	v_mov_b32_e32 v31, v0
	v_mov_b32_e32 v40, v0
	v_mov_b32_e32 v41, v0
	v_mov_b32_e32 v42, v0
	v_mov_b32_e32 v43, v0
	v_mov_b32_e32 v44, v0
	v_mov_b32_e32 v45, v0
	v_mov_b32_e32 v46, v0
	v_mov_b32_e32 v47, v0
	v_mov_b32_e32 v56, v0
	v_mov_b32_e32 v57, v0
	v_mov_b32_e32 v58, v0
	v_mov_b32_e32 v59, v0
	v_mov_b32_e32 v60, v0
	v_mov_b32_e32 v61, v0
	v_mov_b32_e32 v62, v0
	v_mov_b32_e32 v63, v0
	v_mov_b32_e32 v72, v0
	v_mov_b32_e32 v73, v0
	v_mov_b32_e32 v74, v0
	v_mov_b32_e32 v75, v0
	v_mov_b32_e32 v76, v0
	v_mov_b32_e32 v77, v0
	v_mov_b32_e32 v78, v0
	v_mov_b32_e32 v79, v0
	v_mov_b32_e32 v98, v0
	v_mov_b32_e32 v99, v0
	v_mov_b32_e32 v100, v0
	v_mov_b32_e32 v101, v0
	v_mov_b32_e32 v102, v0
	v_mov_b32_e32 v103, v0
	v_mov_b32_e32 v104, v0
	v_mov_b32_e32 v105, v0
	v_mov_b32_e32 v122, v0
	v_mov_b32_e32 v123, v0
	v_mov_b32_e32 v124, v0
	v_mov_b32_e32 v125, v0
	v_mov_b32_e32 v126, v0
	v_mov_b32_e32 v127, v0
	v_mov_b32_e32 v128, v0
	v_mov_b32_e32 v129, v0
	v_mov_b32_e32 v146, v0
	v_mov_b32_e32 v147, v0
	v_mov_b32_e32 v148, v0
	v_mov_b32_e32 v149, v0
	v_mov_b32_e32 v150, v0
	v_mov_b32_e32 v151, v0
	v_mov_b32_e32 v152, v0
	v_mov_b32_e32 v153, v0
	v_mov_b32_e32 v80, v0
	v_mov_b32_e32 v81, v0
	v_mov_b32_e32 v82, v0
	v_mov_b32_e32 v83, v0
	v_mov_b32_e32 v84, v0
	v_mov_b32_e32 v85, v0
	v_mov_b32_e32 v86, v0
	v_mov_b32_e32 v87, v0
	v_mov_b32_e32 v114, v0
	v_mov_b32_e32 v115, v0
	v_mov_b32_e32 v116, v0
	v_mov_b32_e32 v117, v0
	v_mov_b32_e32 v118, v0
	v_mov_b32_e32 v119, v0
	v_mov_b32_e32 v120, v0
	v_mov_b32_e32 v121, v0
	v_mov_b32_e32 v138, v0
	v_mov_b32_e32 v139, v0
	v_mov_b32_e32 v140, v0
	v_mov_b32_e32 v141, v0
	v_mov_b32_e32 v142, v0
	v_mov_b32_e32 v143, v0
	v_mov_b32_e32 v144, v0
	v_mov_b32_e32 v145, v0
	v_mov_b32_e32 v154, v0
	v_mov_b32_e32 v155, v0
	v_mov_b32_e32 v156, v0
	v_mov_b32_e32 v157, v0
	v_mov_b32_e32 v158, v0
	v_mov_b32_e32 v159, v0
	v_mov_b32_e32 v160, v0
	v_mov_b32_e32 v161, v0
	v_readfirstlane_b32 s70, v241
	s_nop 3
	s_lshr_b32 s70, s70, 6
	s_cmp_lt_u32 s70, 4
	s_cbranch_scc0 .Lprio_done_593
	s_setprio 1
